# removed dead per-block flag computations from the selected-branch block head
# speedup vs baseline: 1.0100x; 1.0065x over previous
; template <bool SEL> ...
;     ...
;         for (int it = it0; it < it0 + 2 && it < n; ++it) {
;             const int j = jhi - it, slot = it & 3;
;             bool selq[2] = {true, true}; bool any[2] = {true, true};
;             if (SEL) {
; #pragma unroll
;                 for (int cg_ = 0; cg_ < 2; ++cg_) {
;                     const unsigned long long wsel = j < 64 ? sw[cg_][0] : sw[cg_][1];
;                     selq[cg_] = ((wsel >> (j & 63)) & 1ull) != 0ull; any[cg_] = __any(selq[cg_]) != 0;
;                 }
;             }
;             if (any[0] || any[1]) {
;                 const unsigned char* Ks = lds + OFF_RING + slot * SLOTB; const unsigned char* Vs = Ks + 8192;
;                 bf16x8 kf[4][2]; load_kfrags(kf, Ks, r, fq);
;                 const bool edge = (j >= T - 2) || (wl == 512 && j == T - 8);
;                 if (edge) {
.LBB0_2482:
	s_cmp_lt_i32 s48, 64
	s_cselect_b64 vcc, -1, 0
	s_waitcnt lgkmcnt(2)
	v_cndmask_b32_e32 v60, v35, v33, vcc
	s_lshl_b64 s[6:7], 1, s48
	v_cndmask_b32_e32 v62, v34, v32, vcc
	v_and_b32_e32 v61, s7, v60
	v_and_b32_e32 v60, s6, v62
	v_cmp_ne_u64_e64 s[10:11], 0, v[60:61]
	v_cndmask_b32_e32 v60, v39, v37, vcc
	v_cndmask_b32_e32 v62, v38, v36, vcc
	v_and_b32_e32 v61, s7, v60
	v_and_b32_e32 v60, s6, v62
	v_cmp_ne_u64_e64 s[8:9], 0, v[60:61]
	s_or_b64 s[6:7], s[10:11], s[8:9]
	s_cbranch_scc0 .LBB0_2481
	s_and_b32 s6, s49, 0xc000
	v_add_u32_e32 v60, s6, v140
	v_add_u32_e32 v143, v60, v136
	v_add_u32_e32 v142, v60, v137
	ds_read_b128 v[88:91], v143
	ds_read_b128 v[80:83], v143 offset:512
	ds_read_b128 v[84:87], v142
	ds_read_b128 v[76:79], v142 offset:512
	ds_read_b128 v[72:75], v143 offset:4096
	ds_read_b128 v[60:63], v143 offset:4608
	s_waitcnt lgkmcnt(7)
	ds_read_b128 v[68:71], v142 offset:4096
	s_waitcnt lgkmcnt(7)
	ds_read_b128 v[64:67], v142 offset:4608
	s_cmp_lt_i32 s48, s93
	s_cbranch_scc1 .Lsel_int
	s_branch .Lsel_edge
	s_and_b64 vcc, exec, s[38:39]
	s_cbranch_vccz .LBB0_2557
	s_and_b64 vcc, exec, s[36:37]
	s_cbranch_vccz .LBB0_2521
	s_waitcnt lgkmcnt(7)
	v_mfma_f32_16x16x32_bf16 v[92:95], v[88:91], v[10:13], 0
	v_add_u32_e32 v119, s4, v141
	v_add_u32_e32 v110, 4, v119
	v_cmp_gt_u32_e32 vcc, 2.0, v110
	s_waitcnt lgkmcnt(5)
	v_mfma_f32_16x16x32_bf16 v[104:107], v[84:87], v[14:17], v[92:95]
	v_mov_b32_e32 v108, 0xf149f2ca
	v_mov_b32_e32 v109, 0xf149f2ca
	v_mfma_f32_16x16x32_bf16 v[92:95], v[80:83], v[10:13], 0
	s_waitcnt lgkmcnt(4)
	v_mfma_f32_16x16x32_bf16 v[100:103], v[76:79], v[14:17], v[92:95]
	s_waitcnt lgkmcnt(3)
	v_mfma_f32_16x16x32_bf16 v[92:95], v[72:75], v[10:13], 0
	s_waitcnt lgkmcnt(1)
	v_mfma_f32_16x16x32_bf16 v[96:99], v[68:71], v[14:17], v[92:95]
	v_mfma_f32_16x16x32_bf16 v[92:95], v[60:63], v[10:13], 0
	s_waitcnt lgkmcnt(0)
	v_mfma_f32_16x16x32_bf16 v[92:95], v[64:67], v[14:17], v[92:95]
	s_and_saveexec_b64 s[12:13], vcc
	s_cbranch_execz .LBB0_2488
	v_min_u32_e32 v109, 0x80, v110
	v_lshl_add_u32 v109, v109, 6, v177
	ds_read_b32 v109, v109
	s_waitcnt lgkmcnt(0)
	v_add_f32_e32 v109, v104, v109
